# mem-attention unit: key and value image staging pipelined (16 loads in flight instead of 4 trips of 4)
# speedup vs baseline: 1.0028x; 1.0028x over previous
.LBB0_668:
	v_lshl_add_u64 v[254:255], v[74:75], 0, v[68:69]
	global_load_dwordx4 v[82:85], v[254:255], off
	v_lshl_add_u64 v[254:255], v[76:77], 0, v[68:69]
	global_load_dwordx4 v[86:89], v[254:255], off
	v_lshl_add_u64 v[254:255], v[72:73], 0, v[68:69]
	global_load_dwordx4 v[200:203], v[254:255], off
	v_lshl_add_u64 v[254:255], v[70:71], 0, v[68:69]
	global_load_dwordx4 v[204:207], v[254:255], off
	v_lshl_add_u64 v[74:75], v[74:75], 0, s[10:11]
	v_lshl_add_u64 v[76:77], v[76:77], 0, s[10:11]
	v_lshl_add_u64 v[72:73], v[72:73], 0, s[10:11]
	v_lshl_add_u64 v[70:71], v[70:71], 0, s[10:11]
	v_lshl_add_u64 v[254:255], v[74:75], 0, v[68:69]
	global_load_dwordx4 v[208:211], v[254:255], off
	v_lshl_add_u64 v[254:255], v[76:77], 0, v[68:69]
	global_load_dwordx4 v[212:215], v[254:255], off
	v_lshl_add_u64 v[254:255], v[72:73], 0, v[68:69]
	global_load_dwordx4 v[216:219], v[254:255], off
	v_lshl_add_u64 v[254:255], v[70:71], 0, v[68:69]
	global_load_dwordx4 v[220:223], v[254:255], off
	v_lshl_add_u64 v[74:75], v[74:75], 0, s[10:11]
	v_lshl_add_u64 v[76:77], v[76:77], 0, s[10:11]
	v_lshl_add_u64 v[72:73], v[72:73], 0, s[10:11]
	v_lshl_add_u64 v[70:71], v[70:71], 0, s[10:11]
	v_lshl_add_u64 v[254:255], v[74:75], 0, v[68:69]
	global_load_dwordx4 v[224:227], v[254:255], off
	v_lshl_add_u64 v[254:255], v[76:77], 0, v[68:69]
	global_load_dwordx4 v[228:231], v[254:255], off
	v_lshl_add_u64 v[254:255], v[72:73], 0, v[68:69]
	global_load_dwordx4 v[232:235], v[254:255], off
	v_lshl_add_u64 v[254:255], v[70:71], 0, v[68:69]
	global_load_dwordx4 v[236:239], v[254:255], off
	v_lshl_add_u64 v[74:75], v[74:75], 0, s[10:11]
	v_lshl_add_u64 v[76:77], v[76:77], 0, s[10:11]
	v_lshl_add_u64 v[72:73], v[72:73], 0, s[10:11]
	v_lshl_add_u64 v[70:71], v[70:71], 0, s[10:11]
	v_lshl_add_u64 v[254:255], v[74:75], 0, v[68:69]
	global_load_dwordx4 v[240:243], v[254:255], off
	v_lshl_add_u64 v[254:255], v[76:77], 0, v[68:69]
	global_load_dwordx4 v[244:247], v[254:255], off
	v_lshl_add_u64 v[254:255], v[72:73], 0, v[68:69]
	global_load_dwordx4 v[250:253], v[254:255], off
	v_add_u32_e32 v103, v80, v66
	s_waitcnt vmcnt(14)
	ds_write_b128 v103, v[82:85]
	v_lshl_add_u64 v[254:255], v[70:71], 0, v[68:69]
	global_load_dwordx4 v[82:85], v[254:255], off
	v_add_u32_e32 v103, v81, v66
	s_waitcnt vmcnt(14)
	ds_write_b128 v103, v[86:89]
	v_add_u32_e32 v103, v79, v66
	s_waitcnt vmcnt(13)
	ds_write_b128 v103, v[200:203]
	v_add_u32_e32 v103, v78, v66
	s_waitcnt vmcnt(12)
	ds_write_b128 v103, v[204:207]
	v_add_u32_e32 v80, 0x8400, v80
	v_add_u32_e32 v81, 0x8400, v81
	v_add_u32_e32 v79, 0x8400, v79
	v_add_u32_e32 v78, 0x8400, v78
	v_add_u32_e32 v103, v80, v66
	s_waitcnt vmcnt(11)
	ds_write_b128 v103, v[208:211]
	v_add_u32_e32 v103, v81, v66
	s_waitcnt vmcnt(10)
	ds_write_b128 v103, v[212:215]
	v_add_u32_e32 v103, v79, v66
	s_waitcnt vmcnt(9)
	ds_write_b128 v103, v[216:219]
	v_add_u32_e32 v103, v78, v66
	s_waitcnt vmcnt(8)
	ds_write_b128 v103, v[220:223]
	v_add_u32_e32 v80, 0x8400, v80
	v_add_u32_e32 v81, 0x8400, v81
	v_add_u32_e32 v79, 0x8400, v79
	v_add_u32_e32 v78, 0x8400, v78
	v_add_u32_e32 v103, v80, v66
	s_waitcnt vmcnt(7)
	ds_write_b128 v103, v[224:227]
	v_add_u32_e32 v103, v81, v66
	s_waitcnt vmcnt(6)
	ds_write_b128 v103, v[228:231]
	v_add_u32_e32 v103, v79, v66
	s_waitcnt vmcnt(5)
	ds_write_b128 v103, v[232:235]
	v_add_u32_e32 v103, v78, v66
	s_waitcnt vmcnt(4)
	ds_write_b128 v103, v[236:239]
	v_add_u32_e32 v80, 0x8400, v80
	v_add_u32_e32 v81, 0x8400, v81
	v_add_u32_e32 v79, 0x8400, v79
	v_add_u32_e32 v78, 0x8400, v78
	v_add_u32_e32 v103, v80, v66
	s_waitcnt vmcnt(3)
	ds_write_b128 v103, v[240:243]
	v_add_u32_e32 v103, v81, v66
	s_waitcnt vmcnt(2)
	ds_write_b128 v103, v[244:247]
	v_add_u32_e32 v103, v79, v66
	s_waitcnt vmcnt(1)
	ds_write_b128 v103, v[250:253]
	v_add_u32_e32 v103, v78, v66
	s_waitcnt vmcnt(0)
	ds_write_b128 v103, v[82:85]
	s_or_b64 exec, exec, s[20:21]
	v_mul_f32_e32 v68, 0x3d800000, v6
	v_mul_f32_e32 v69, 0x3d800000, v7
	v_max3_f32 v68, v68, s41, v69
	v_mul_f32_e32 v69, 0x3d800000, v8
	v_mul_f32_e32 v70, 0x3d800000, v9
	v_max3_f32 v68, v68, v69, v70
	v_mul_f32_e32 v69, 0x3d800000, v2
	v_mul_f32_e32 v70, 0x3d800000, v3
	v_max3_f32 v68, v68, v69, v70
	v_mul_f32_e32 v69, 0x3d800000, v4
	v_mul_f32_e32 v70, 0x3d800000, v5
	v_max3_f32 v68, v68, v69, v70
	v_mul_f32_e32 v69, 0x3d800000, v10
	v_mul_f32_e32 v70, 0x3d800000, v11
	v_max3_f32 v68, v68, v69, v70
	v_mul_f32_e32 v69, 0x3d800000, v12
	v_mul_f32_e32 v70, 0x3d800000, v13
	v_max3_f32 v68, v68, v69, v70
	v_mul_f32_e32 v69, 0x3d800000, v14
	v_mul_f32_e32 v70, 0x3d800000, v15
	v_max3_f32 v68, v68, v69, v70
	v_mul_f32_e32 v69, 0x3d800000, v16
	v_mul_f32_e32 v70, 0x3d800000, v17
	v_max3_f32 v68, v68, v69, v70
	v_mul_f32_e32 v69, 0x3d800000, v18
	v_mul_f32_e32 v70, 0x3d800000, v19
	v_max3_f32 v68, v68, v69, v70
	v_mul_f32_e32 v69, 0x3d800000, v20
	v_mul_f32_e32 v70, 0x3d800000, v21
	v_max3_f32 v68, v68, v69, v70
	v_mul_f32_e32 v69, 0x3d800000, v22
	v_mul_f32_e32 v70, 0x3d800000, v23
	v_max3_f32 v68, v68, v69, v70
	v_mul_f32_e32 v69, 0x3d800000, v24
	v_mul_f32_e32 v70, 0x3d800000, v25
	v_max3_f32 v68, v68, v69, v70
	v_mul_f32_e32 v69, 0x3d800000, v26
	v_mul_f32_e32 v70, 0x3d800000, v27
	v_max3_f32 v68, v68, v69, v70
	v_mul_f32_e32 v69, 0x3d800000, v28
	v_mul_f32_e32 v70, 0x3d800000, v29
	v_max3_f32 v68, v68, v69, v70
	v_mul_f32_e32 v69, 0x3d800000, v30
	v_mul_f32_e32 v70, 0x3d800000, v31
	v_max3_f32 v68, v68, v69, v70
	v_mul_f32_e32 v69, 0x3d800000, v32
	v_mul_f32_e32 v70, 0x3d800000, v33
	v_max3_f32 v68, v68, v69, v70
	v_mul_f32_e32 v69, 0x3d800000, v34
	v_mul_f32_e32 v70, 0x3d800000, v35
	v_max3_f32 v68, v68, v69, v70
	v_mul_f32_e32 v69, 0x3d800000, v36
	v_mul_f32_e32 v70, 0x3d800000, v37
	v_max3_f32 v68, v68, v69, v70
	v_mul_f32_e32 v69, 0x3d800000, v38
	v_mul_f32_e32 v70, 0x3d800000, v39
	v_max3_f32 v68, v68, v69, v70
	v_mul_f32_e32 v69, 0x3d800000, v40
	v_mul_f32_e32 v70, 0x3d800000, v41
	v_max3_f32 v68, v68, v69, v70
	v_mul_f32_e32 v69, 0x3d800000, v42
	v_mul_f32_e32 v70, 0x3d800000, v43
	v_max3_f32 v68, v68, v69, v70
	v_mul_f32_e32 v69, 0x3d800000, v44
	v_mul_f32_e32 v70, 0x3d800000, v45
	v_max3_f32 v68, v68, v69, v70
	v_mul_f32_e32 v69, 0x3d800000, v46
	v_mul_f32_e32 v70, 0x3d800000, v47
	v_max3_f32 v68, v68, v69, v70
	v_mul_f32_e32 v69, 0x3d800000, v48
	v_mul_f32_e32 v70, 0x3d800000, v49
	v_max3_f32 v68, v68, v69, v70
	v_mul_f32_e32 v69, 0x3d800000, v50
	v_mul_f32_e32 v70, 0x3d800000, v51
	v_max3_f32 v68, v68, v69, v70
	v_mul_f32_e32 v69, 0x3d800000, v52
	v_mul_f32_e32 v70, 0x3d800000, v53
	v_max3_f32 v68, v68, v69, v70
	v_mul_f32_e32 v69, 0x3d800000, v54
	v_mul_f32_e32 v70, 0x3d800000, v55
	v_max3_f32 v68, v68, v69, v70
	v_mul_f32_e32 v69, 0x3d800000, v56
	v_mul_f32_e32 v70, 0x3d800000, v57
	v_max3_f32 v68, v68, v69, v70
	v_mul_f32_e32 v69, 0x3d800000, v58
	v_mul_f32_e32 v70, 0x3d800000, v59
	v_max3_f32 v68, v68, v69, v70
	v_mul_f32_e32 v69, 0x3d800000, v60
	v_mul_f32_e32 v70, 0x3d800000, v61
	v_max3_f32 v68, v68, v69, v70
	v_mul_f32_e32 v69, 0x3d800000, v62
	v_mul_f32_e32 v70, 0x3d800000, v63
	v_max3_f32 v68, v68, v69, v70
	v_mul_f32_e32 v69, 0x3d800000, v64
	v_mul_f32_e32 v70, 0x3d800000, v65
	v_max3_f32 v68, v68, v69, v70
	v_and_b32_e32 v70, 64, v189
	v_xor_b32_e32 v69, 16, v189
	v_add_u32_e32 v70, 64, v70
	v_cmp_lt_i32_e32 vcc, v69, v70
	s_lshl_b32 s20, s45, 8
	v_or_b32_e32 v74, s20, v183
	v_cndmask_b32_e32 v69, v189, v69, vcc
	v_lshlrev_b32_e32 v69, 2, v69
	ds_bpermute_b32 v71, v69, v68
	s_or_b32 s0, s46, 64
	s_and_b32 s21, s36, 0xf80
	v_add_lshl_u32 v72, v182, s20, 8
	v_add_lshl_u32 v66, v177, s20, 8
	s_waitcnt lgkmcnt(0)
	v_max_f32_e32 v71, v71, v71
	v_max_f32_e32 v75, v68, v71
	v_xor_b32_e32 v68, 32, v189
	v_cmp_lt_i32_e32 vcc, v68, v70
	v_lshlrev_b32_e32 v70, 1, v74
	v_and_b32_e32 v72, 0x1fc000, v72
	v_cndmask_b32_e32 v68, v189, v68, vcc
	v_lshlrev_b32_e32 v80, 2, v68
	ds_bpermute_b32 v76, v80, v75
	v_mov_b32_e32 v73, v91
	v_and_b32_e32 v90, 0x1fc000, v66
	v_or_b32_e32 v66, s20, v181
	v_add_lshl_u32 v68, v185, s20, 8
	s_waitcnt lgkmcnt(0)
	v_max_f32_e32 v74, v76, v76
	v_max_f32_e32 v78, v75, v74
	v_fma_f32 v2, v2, s40, -v78
	v_mul_f32_e32 v2, 0x3fb8aa3b, v2
	v_exp_f32_e32 v74, v2
	v_fma_f32 v2, v3, s40, -v78
	v_mul_f32_e32 v2, 0x3fb8aa3b, v2
	v_exp_f32_e32 v75, v2
	v_fma_f32 v2, v4, s40, -v78
	v_mul_f32_e32 v2, 0x3fb8aa3b, v2
	v_exp_f32_e32 v76, v2
	v_fma_f32 v2, v5, s40, -v78
	v_mul_f32_e32 v2, 0x3fb8aa3b, v2
	v_exp_f32_e32 v77, v2
	v_fma_f32 v2, v10, s40, -v78
	v_mul_f32_e32 v2, 0x3fb8aa3b, v2
	v_exp_f32_e32 v10, v2
	v_fma_f32 v2, v11, s40, -v78
	v_mul_f32_e32 v2, 0x3fb8aa3b, v2
	v_exp_f32_e32 v11, v2
	v_fma_f32 v2, v12, s40, -v78
	v_mul_f32_e32 v2, 0x3fb8aa3b, v2
	v_exp_f32_e32 v12, v2
	v_fma_f32 v2, v13, s40, -v78
	v_mul_f32_e32 v2, 0x3fb8aa3b, v2
	v_exp_f32_e32 v13, v2
	v_fma_f32 v2, v14, s40, -v78
	v_mul_f32_e32 v2, 0x3fb8aa3b, v2
	v_exp_f32_e32 v14, v2
	v_fma_f32 v2, v15, s40, -v78
	v_mul_f32_e32 v2, 0x3fb8aa3b, v2
	v_exp_f32_e32 v15, v2
	v_fma_f32 v2, v16, s40, -v78
	v_mul_f32_e32 v2, 0x3fb8aa3b, v2
	v_exp_f32_e32 v16, v2
	v_fma_f32 v2, v17, s40, -v78
	v_mul_f32_e32 v2, 0x3fb8aa3b, v2
	v_exp_f32_e32 v17, v2
	v_fma_f32 v2, v18, s40, -v78
	v_mul_f32_e32 v2, 0x3fb8aa3b, v2
	v_exp_f32_e32 v18, v2
	v_fma_f32 v2, v19, s40, -v78
	v_mul_f32_e32 v2, 0x3fb8aa3b, v2
	v_exp_f32_e32 v19, v2
	v_fma_f32 v2, v20, s40, -v78
	v_mul_f32_e32 v2, 0x3fb8aa3b, v2
	v_exp_f32_e32 v20, v2
	v_fma_f32 v2, v21, s40, -v78
	v_mul_f32_e32 v2, 0x3fb8aa3b, v2
	v_exp_f32_e32 v21, v2
	v_fma_f32 v2, v22, s40, -v78
	v_mul_f32_e32 v2, 0x3fb8aa3b, v2
	v_exp_f32_e32 v22, v2
	v_fma_f32 v2, v23, s40, -v78
	v_mul_f32_e32 v2, 0x3fb8aa3b, v2
	v_exp_f32_e32 v23, v2
	v_fma_f32 v2, v24, s40, -v78
	v_mul_f32_e32 v2, 0x3fb8aa3b, v2
	v_exp_f32_e32 v24, v2
	v_fma_f32 v2, v25, s40, -v78
	v_mul_f32_e32 v2, 0x3fb8aa3b, v2
	v_exp_f32_e32 v25, v2
	v_fma_f32 v2, v26, s40, -v78
	v_mul_f32_e32 v2, 0x3fb8aa3b, v2
	v_exp_f32_e32 v26, v2
	v_fma_f32 v2, v27, s40, -v78
	v_mul_f32_e32 v2, 0x3fb8aa3b, v2
	v_exp_f32_e32 v27, v2
	v_fma_f32 v2, v28, s40, -v78
	v_mul_f32_e32 v2, 0x3fb8aa3b, v2
	v_exp_f32_e32 v28, v2
	v_fma_f32 v2, v29, s40, -v78
	v_mul_f32_e32 v2, 0x3fb8aa3b, v2
	v_exp_f32_e32 v29, v2
	v_fma_f32 v2, v30, s40, -v78
	v_mul_f32_e32 v2, 0x3fb8aa3b, v2
	v_exp_f32_e32 v30, v2
	v_fma_f32 v2, v31, s40, -v78
	v_mul_f32_e32 v2, 0x3fb8aa3b, v2
	v_exp_f32_e32 v31, v2
	v_fma_f32 v2, v32, s40, -v78
	v_mul_f32_e32 v2, 0x3fb8aa3b, v2
	v_exp_f32_e32 v32, v2
	v_fma_f32 v2, v33, s40, -v78
	v_mul_f32_e32 v2, 0x3fb8aa3b, v2
	v_exp_f32_e32 v33, v2
	v_fma_f32 v2, v34, s40, -v78
	v_mul_f32_e32 v2, 0x3fb8aa3b, v2
	v_exp_f32_e32 v34, v2
	v_fma_f32 v2, v35, s40, -v78
	v_mul_f32_e32 v2, 0x3fb8aa3b, v2
	v_exp_f32_e32 v35, v2
	v_fma_f32 v2, v36, s40, -v78
	v_mul_f32_e32 v2, 0x3fb8aa3b, v2
	v_exp_f32_e32 v36, v2
	v_fma_f32 v2, v37, s40, -v78
	v_mul_f32_e32 v2, 0x3fb8aa3b, v2
	v_exp_f32_e32 v37, v2
	v_fma_f32 v2, v38, s40, -v78
	v_mul_f32_e32 v2, 0x3fb8aa3b, v2
	v_exp_f32_e32 v38, v2
	v_fma_f32 v2, v39, s40, -v78
	v_mul_f32_e32 v2, 0x3fb8aa3b, v2
	v_exp_f32_e32 v39, v2
	v_fma_f32 v2, v40, s40, -v78
	v_mul_f32_e32 v2, 0x3fb8aa3b, v2
	v_exp_f32_e32 v40, v2
	v_fma_f32 v2, v41, s40, -v78
	v_mul_f32_e32 v2, 0x3fb8aa3b, v2
	v_exp_f32_e32 v41, v2
	v_fma_f32 v2, v42, s40, -v78
	v_mul_f32_e32 v2, 0x3fb8aa3b, v2
	v_exp_f32_e32 v42, v2
	v_fma_f32 v2, v43, s40, -v78
	v_mul_f32_e32 v2, 0x3fb8aa3b, v2
	v_exp_f32_e32 v43, v2
	v_fma_f32 v2, v44, s40, -v78
	v_mul_f32_e32 v2, 0x3fb8aa3b, v2
	v_exp_f32_e32 v44, v2
	v_fma_f32 v2, v45, s40, -v78
	v_mul_f32_e32 v2, 0x3fb8aa3b, v2
	v_exp_f32_e32 v45, v2
	v_fma_f32 v2, v46, s40, -v78
	v_mul_f32_e32 v2, 0x3fb8aa3b, v2
	v_exp_f32_e32 v46, v2
	v_fma_f32 v2, v47, s40, -v78
	v_mul_f32_e32 v2, 0x3fb8aa3b, v2
	v_exp_f32_e32 v47, v2
	v_fma_f32 v2, v48, s40, -v78
	v_mul_f32_e32 v2, 0x3fb8aa3b, v2
	v_exp_f32_e32 v48, v2
	v_fma_f32 v2, v49, s40, -v78
	v_mul_f32_e32 v2, 0x3fb8aa3b, v2
	v_exp_f32_e32 v49, v2
	v_fma_f32 v2, v50, s40, -v78
	v_mul_f32_e32 v2, 0x3fb8aa3b, v2
	v_exp_f32_e32 v50, v2
	v_fma_f32 v2, v51, s40, -v78
	v_mul_f32_e32 v2, 0x3fb8aa3b, v2
	v_exp_f32_e32 v51, v2
	v_fma_f32 v2, v52, s40, -v78
	v_mul_f32_e32 v2, 0x3fb8aa3b, v2
	v_exp_f32_e32 v52, v2
	v_fma_f32 v2, v53, s40, -v78
	v_mul_f32_e32 v2, 0x3fb8aa3b, v2
	v_exp_f32_e32 v53, v2
	v_fma_f32 v2, v54, s40, -v78
	v_mul_f32_e32 v2, 0x3fb8aa3b, v2
	v_exp_f32_e32 v54, v2
	v_fma_f32 v2, v55, s40, -v78
	v_mul_f32_e32 v2, 0x3fb8aa3b, v2
	v_exp_f32_e32 v55, v2
	v_fma_f32 v2, v56, s40, -v78
	v_mul_f32_e32 v2, 0x3fb8aa3b, v2
	v_exp_f32_e32 v56, v2
	v_fma_f32 v2, v57, s40, -v78
	v_mul_f32_e32 v2, 0x3fb8aa3b, v2
	v_exp_f32_e32 v57, v2
	v_fma_f32 v2, v58, s40, -v78
	v_mul_f32_e32 v2, 0x3fb8aa3b, v2
	v_exp_f32_e32 v58, v2
	v_fma_f32 v2, v59, s40, -v78
	v_mul_f32_e32 v2, 0x3fb8aa3b, v2
	v_exp_f32_e32 v59, v2
	v_fma_f32 v2, v60, s40, -v78
	v_mul_f32_e32 v2, 0x3fb8aa3b, v2
	v_exp_f32_e32 v60, v2
	v_fma_f32 v2, v61, s40, -v78
	v_mul_f32_e32 v2, 0x3fb8aa3b, v2
	v_exp_f32_e32 v61, v2
	v_fma_f32 v2, v62, s40, -v78
	v_mul_f32_e32 v2, 0x3fb8aa3b, v2
	v_fma_f32 v6, v6, s40, -v78
	v_exp_f32_e32 v62, v2
	v_fma_f32 v2, v63, s40, -v78
	v_mul_f32_e32 v6, 0x3fb8aa3b, v6
	v_fma_f32 v7, v7, s40, -v78
	v_mul_f32_e32 v2, 0x3fb8aa3b, v2
	v_exp_f32_e32 v6, v6
	v_mul_f32_e32 v7, 0x3fb8aa3b, v7
	v_fma_f32 v8, v8, s40, -v78
	v_exp_f32_e32 v63, v2
	v_fma_f32 v2, v64, s40, -v78
	v_exp_f32_e32 v7, v7
	v_mul_f32_e32 v8, 0x3fb8aa3b, v8
	v_fma_f32 v9, v9, s40, -v78
	v_mul_f32_e32 v2, 0x3fb8aa3b, v2
	v_exp_f32_e32 v8, v8
	v_mul_f32_e32 v9, 0x3fb8aa3b, v9
	v_exp_f32_e32 v64, v2
	v_fma_f32 v2, v65, s40, -v78
	v_exp_f32_e32 v9, v9
	v_mul_f32_e32 v2, 0x3fb8aa3b, v2
	v_exp_f32_e32 v65, v2
	v_add_f32_e32 v2, 0, v6
	v_add_f32_e32 v2, v7, v2
	v_add_f32_e32 v2, v8, v2
	v_add_f32_e32 v2, v9, v2
	v_add_f32_e32 v2, v74, v2
	v_add_f32_e32 v2, v75, v2
	v_add_f32_e32 v2, v76, v2
	v_add_f32_e32 v2, v77, v2
	v_add_f32_e32 v2, v10, v2
	v_add_f32_e32 v2, v11, v2
	v_add_f32_e32 v2, v12, v2
	v_add_f32_e32 v2, v13, v2
	v_add_f32_e32 v2, v14, v2
	v_add_f32_e32 v2, v15, v2
	v_add_f32_e32 v2, v16, v2
	v_add_f32_e32 v2, v17, v2
	v_add_f32_e32 v2, v18, v2
	v_add_f32_e32 v2, v19, v2
	v_add_f32_e32 v2, v20, v2
	v_add_f32_e32 v2, v21, v2
	v_add_f32_e32 v2, v22, v2
	v_add_f32_e32 v2, v23, v2
	v_add_f32_e32 v2, v24, v2
	v_add_f32_e32 v2, v25, v2
	v_add_f32_e32 v2, v26, v2
	v_add_f32_e32 v2, v27, v2
	v_add_f32_e32 v2, v28, v2
	v_add_f32_e32 v2, v29, v2
	v_add_f32_e32 v2, v30, v2
	v_add_f32_e32 v2, v31, v2
	v_add_f32_e32 v2, v32, v2
	v_add_f32_e32 v2, v33, v2
	v_add_f32_e32 v2, v34, v2
	v_add_f32_e32 v2, v35, v2
	v_add_f32_e32 v2, v36, v2
	v_add_f32_e32 v2, v37, v2
	v_add_f32_e32 v2, v38, v2
	v_add_f32_e32 v2, v39, v2
	v_add_f32_e32 v2, v40, v2
	v_add_f32_e32 v2, v41, v2
	v_add_f32_e32 v2, v42, v2
	v_add_f32_e32 v2, v43, v2
	v_add_f32_e32 v2, v44, v2
	v_add_f32_e32 v2, v45, v2
	v_add_f32_e32 v2, v46, v2
	v_add_f32_e32 v2, v47, v2
	v_add_f32_e32 v2, v48, v2
	v_add_f32_e32 v2, v49, v2
	v_add_f32_e32 v2, v50, v2
	v_add_f32_e32 v2, v51, v2
	v_add_f32_e32 v2, v52, v2
	v_add_f32_e32 v2, v53, v2
	v_add_f32_e32 v2, v54, v2
	v_add_f32_e32 v2, v55, v2
	v_add_f32_e32 v2, v56, v2
	v_add_f32_e32 v2, v57, v2
	v_add_f32_e32 v2, v58, v2
	v_add_f32_e32 v2, v59, v2
	v_add_f32_e32 v2, v60, v2
	v_add_f32_e32 v2, v61, v2
	v_add_f32_e32 v2, v62, v2
	v_add_f32_e32 v2, v63, v2
	v_add_f32_e32 v2, v64, v2
	v_add_f32_e32 v2, v65, v2
	ds_bpermute_b32 v3, v69, v2
	v_or_b32_e32 v4, s20, v186
	v_lshlrev_b32_e32 v78, 1, v4
	v_or_b32_e32 v4, s20, v173
	v_mov_b32_e32 v83, v91
	s_waitcnt lgkmcnt(0)
	v_add_f32_e32 v2, v2, v3
	ds_bpermute_b32 v3, v80, v2
	v_lshlrev_b32_e32 v80, 1, v4
	v_add_lshl_u32 v4, v187, s20, 8
	v_and_b32_e32 v82, 0x1fc000, v4
	v_lshlrev_b32_e32 v66, 1, v66
	s_waitcnt lgkmcnt(0)
	v_add_f32_e32 v2, v2, v3
	v_div_scale_f32 v3, s[22:23], v2, v2, 1.0
	v_rcp_f32_e32 v5, v3
	s_ashr_i32 s22, s44, 7
	s_ashr_i32 s23, s22, 31
	s_lshl_b64 s[22:23], s[22:23], 20
	v_fma_f32 v4, -v3, v5, 1.0
	v_fmac_f32_e32 v5, v4, v5
	v_div_scale_f32 v4, vcc, 1.0, v2, 1.0
	v_mul_f32_e32 v84, v4, v5
	v_fma_f32 v85, -v3, v84, v4
	v_fmac_f32_e32 v84, v85, v5
	v_fma_f32 v3, -v3, v84, v4
	v_div_fmas_f32 v3, v3, v5, v84
	v_div_fixup_f32 v84, v3, v2, 1.0
	v_pk_mul_f32 v[2:3], v[6:7], v[84:85] op_sel_hi:[1,0]
	v_pk_mul_f32 v[4:5], v[8:9], v[84:85] op_sel_hi:[1,0]
	v_cvt_pk_bf16_f32 v2, v2, v3
	v_cvt_pk_bf16_f32 v3, v4, v5
	v_pk_mul_f32 v[4:5], v[74:75], v[84:85] op_sel_hi:[1,0]
	v_pk_mul_f32 v[6:7], v[76:77], v[84:85] op_sel_hi:[1,0]
	v_cvt_pk_bf16_f32 v4, v4, v5
	v_cvt_pk_bf16_f32 v5, v6, v7
	v_pk_mul_f32 v[6:7], v[10:11], v[84:85] op_sel_hi:[1,0]
	v_pk_mul_f32 v[8:9], v[12:13], v[84:85] op_sel_hi:[1,0]
	v_cvt_pk_bf16_f32 v6, v6, v7
	v_cvt_pk_bf16_f32 v7, v8, v9
	v_pk_mul_f32 v[8:9], v[14:15], v[84:85] op_sel_hi:[1,0]
	v_pk_mul_f32 v[10:11], v[16:17], v[84:85] op_sel_hi:[1,0]
	v_cvt_pk_bf16_f32 v8, v8, v9
	v_cvt_pk_bf16_f32 v9, v10, v11
	v_pk_mul_f32 v[10:11], v[18:19], v[84:85] op_sel_hi:[1,0]
	v_pk_mul_f32 v[12:13], v[20:21], v[84:85] op_sel_hi:[1,0]
	v_cvt_pk_bf16_f32 v10, v10, v11
	v_cvt_pk_bf16_f32 v11, v12, v13
	v_pk_mul_f32 v[12:13], v[22:23], v[84:85] op_sel_hi:[1,0]
	v_pk_mul_f32 v[14:15], v[24:25], v[84:85] op_sel_hi:[1,0]
	v_cvt_pk_bf16_f32 v12, v12, v13
	v_cvt_pk_bf16_f32 v13, v14, v15
	v_pk_mul_f32 v[14:15], v[26:27], v[84:85] op_sel_hi:[1,0]
	v_pk_mul_f32 v[16:17], v[28:29], v[84:85] op_sel_hi:[1,0]
	v_cvt_pk_bf16_f32 v14, v14, v15
	v_cvt_pk_bf16_f32 v15, v16, v17
	v_pk_mul_f32 v[16:17], v[30:31], v[84:85] op_sel_hi:[1,0]
	v_pk_mul_f32 v[18:19], v[32:33], v[84:85] op_sel_hi:[1,0]
	v_cvt_pk_bf16_f32 v16, v16, v17
	v_cvt_pk_bf16_f32 v17, v18, v19
	v_pk_mul_f32 v[18:19], v[34:35], v[84:85] op_sel_hi:[1,0]
	v_pk_mul_f32 v[20:21], v[36:37], v[84:85] op_sel_hi:[1,0]
	v_cvt_pk_bf16_f32 v18, v18, v19
	v_cvt_pk_bf16_f32 v19, v20, v21
	v_pk_mul_f32 v[20:21], v[38:39], v[84:85] op_sel_hi:[1,0]
	v_pk_mul_f32 v[22:23], v[40:41], v[84:85] op_sel_hi:[1,0]
	v_cvt_pk_bf16_f32 v20, v20, v21
	v_cvt_pk_bf16_f32 v21, v22, v23
	v_pk_mul_f32 v[22:23], v[42:43], v[84:85] op_sel_hi:[1,0]
	v_pk_mul_f32 v[24:25], v[44:45], v[84:85] op_sel_hi:[1,0]
	v_cvt_pk_bf16_f32 v22, v22, v23
	v_cvt_pk_bf16_f32 v23, v24, v25
	v_pk_mul_f32 v[24:25], v[46:47], v[84:85] op_sel_hi:[1,0]
	v_pk_mul_f32 v[26:27], v[48:49], v[84:85] op_sel_hi:[1,0]
	v_cvt_pk_bf16_f32 v24, v24, v25
	v_cvt_pk_bf16_f32 v25, v26, v27
	v_pk_mul_f32 v[26:27], v[50:51], v[84:85] op_sel_hi:[1,0]
	v_pk_mul_f32 v[28:29], v[52:53], v[84:85] op_sel_hi:[1,0]
	v_cvt_pk_bf16_f32 v26, v26, v27
	v_cvt_pk_bf16_f32 v27, v28, v29
	v_pk_mul_f32 v[28:29], v[54:55], v[84:85] op_sel_hi:[1,0]
	v_pk_mul_f32 v[30:31], v[56:57], v[84:85] op_sel_hi:[1,0]
	s_add_u32 s24, s22, 0xf000400
	v_cvt_pk_bf16_f32 v28, v28, v29
	v_cvt_pk_bf16_f32 v29, v30, v31
	v_pk_mul_f32 v[30:31], v[58:59], v[84:85] op_sel_hi:[1,0]
	v_pk_mul_f32 v[32:33], v[60:61], v[84:85] op_sel_hi:[1,0]
	s_addc_u32 s25, s23, 0
	s_add_i32 s21, s21, s43
	v_cvt_pk_bf16_f32 v30, v30, v31
	v_cvt_pk_bf16_f32 v31, v32, v33
	v_pk_mul_f32 v[32:33], v[62:63], v[84:85] op_sel_hi:[1,0]
	v_pk_mul_f32 v[34:35], v[64:65], v[84:85] op_sel_hi:[1,0]
	v_add_u32_e32 v40, s21, v180
	v_cvt_pk_bf16_f32 v32, v32, v33
	v_cvt_pk_bf16_f32 v33, v34, v35
	v_lshlrev_b32_e32 v34, 6, v190
	v_mad_i64_i32 v[46:47], s[26:27], v40, s39, v[104:105]
	v_lshlrev_b32_e32 v40, 2, v40
	v_and_b32_e32 v50, 0x3c0, v34
	v_lshlrev_b32_e32 v34, 2, v190
	v_lshl_add_u64 v[38:39], s[24:25], 0, v[72:73]
	v_and_b32_e32 v52, 32, v40
	s_add_u32 s22, s22, 0xf000000
	v_and_b32_e32 v51, 32, v34
	v_lshl_add_u64 v[34:35], s[24:25], 0, v[90:91]
	v_and_or_b32 v38, v70, 24, v38
	v_add_u32_e32 v90, v184, v52
	s_addc_u32 s23, s23, 0
	v_mov_b32_e32 v67, v91
	v_mov_b32_e32 v71, v91
	v_and_b32_e32 v68, 0x1fc000, v68
	v_mov_b32_e32 v69, v91
	v_mov_b32_e32 v79, v91
	v_mov_b32_e32 v81, v91
	v_lshl_add_u64 v[38:39], v[38:39], 0, v[90:91]
	v_lshl_add_u64 v[48:49], s[22:23], 0, v[82:83]
	v_add_u32_e32 v90, v188, v52
	s_mov_b32 s20, 16
	v_lshl_add_u64 v[36:37], v[46:47], 0, v[66:67]
	v_lshl_add_u64 v[40:41], v[46:47], 0, v[70:71]
	v_lshl_add_u64 v[42:43], s[22:23], 0, v[68:69]
	v_lshl_add_u64 v[44:45], v[46:47], 0, v[78:79]
	v_lshl_add_u64 v[46:47], v[46:47], 0, v[80:81]
	v_lshl_add_u64 v[48:49], v[48:49], 0, v[90:91]
	v_mov_b32_e32 v52, v107
	v_lshl_add_u64 v[234:235], s[92:93], 0, v[46:47]
	global_load_dwordx2 v[200:201], v[234:235], off
	global_load_dwordx2 v[208:209], v[234:235], off offset:128
	global_load_dwordx2 v[216:217], v[234:235], off offset:256
	global_load_dwordx2 v[224:225], v[234:235], off offset:384
	v_lshl_add_u64 v[234:235], s[92:93], 0, v[44:45]
	global_load_dwordx2 v[202:203], v[234:235], off
	global_load_dwordx2 v[210:211], v[234:235], off offset:128
	global_load_dwordx2 v[218:219], v[234:235], off offset:256
	global_load_dwordx2 v[226:227], v[234:235], off offset:384
	v_lshl_add_u64 v[234:235], s[92:93], 0, v[40:41]
	global_load_dwordx2 v[204:205], v[234:235], off
	global_load_dwordx2 v[212:213], v[234:235], off offset:128
	global_load_dwordx2 v[220:221], v[234:235], off offset:256
	global_load_dwordx2 v[228:229], v[234:235], off offset:384
	v_lshl_add_u64 v[234:235], s[92:93], 0, v[36:37]
	global_load_dwordx2 v[206:207], v[234:235], off
	global_load_dwordx2 v[214:215], v[234:235], off offset:128
	global_load_dwordx2 v[222:223], v[234:235], off offset:256
	global_load_dwordx2 v[230:231], v[234:235], off offset:384
	s_barrier

.LBB0_1451:
	v_lshl_add_u64 v[254:255], v[76:77], 0, v[68:69]
	global_load_dwordx4 v[82:85], v[254:255], off
	v_lshl_add_u64 v[254:255], v[74:75], 0, v[68:69]
	global_load_dwordx4 v[86:89], v[254:255], off
	v_lshl_add_u64 v[254:255], v[72:73], 0, v[68:69]
	global_load_dwordx4 v[200:203], v[254:255], off
	v_lshl_add_u64 v[254:255], v[70:71], 0, v[68:69]
	global_load_dwordx4 v[204:207], v[254:255], off
	v_lshl_add_u64 v[76:77], v[76:77], 0, s[10:11]
	v_lshl_add_u64 v[74:75], v[74:75], 0, s[10:11]
	v_lshl_add_u64 v[72:73], v[72:73], 0, s[10:11]
	v_lshl_add_u64 v[70:71], v[70:71], 0, s[10:11]
	v_lshl_add_u64 v[254:255], v[76:77], 0, v[68:69]
	global_load_dwordx4 v[208:211], v[254:255], off
	v_lshl_add_u64 v[254:255], v[74:75], 0, v[68:69]
	global_load_dwordx4 v[212:215], v[254:255], off
	v_lshl_add_u64 v[254:255], v[72:73], 0, v[68:69]
	global_load_dwordx4 v[216:219], v[254:255], off
	v_lshl_add_u64 v[254:255], v[70:71], 0, v[68:69]
	global_load_dwordx4 v[220:223], v[254:255], off
	v_lshl_add_u64 v[76:77], v[76:77], 0, s[10:11]
	v_lshl_add_u64 v[74:75], v[74:75], 0, s[10:11]
	v_lshl_add_u64 v[72:73], v[72:73], 0, s[10:11]
	v_lshl_add_u64 v[70:71], v[70:71], 0, s[10:11]
	v_lshl_add_u64 v[254:255], v[76:77], 0, v[68:69]
	global_load_dwordx4 v[224:227], v[254:255], off
	v_lshl_add_u64 v[254:255], v[74:75], 0, v[68:69]
	global_load_dwordx4 v[228:231], v[254:255], off
	v_lshl_add_u64 v[254:255], v[72:73], 0, v[68:69]
	global_load_dwordx4 v[232:235], v[254:255], off
	v_lshl_add_u64 v[254:255], v[70:71], 0, v[68:69]
	global_load_dwordx4 v[236:239], v[254:255], off
	v_lshl_add_u64 v[76:77], v[76:77], 0, s[10:11]
	v_lshl_add_u64 v[74:75], v[74:75], 0, s[10:11]
	v_lshl_add_u64 v[72:73], v[72:73], 0, s[10:11]
	v_lshl_add_u64 v[70:71], v[70:71], 0, s[10:11]
	v_lshl_add_u64 v[254:255], v[76:77], 0, v[68:69]
	global_load_dwordx4 v[240:243], v[254:255], off
	v_lshl_add_u64 v[254:255], v[74:75], 0, v[68:69]
	global_load_dwordx4 v[244:247], v[254:255], off
	v_lshl_add_u64 v[254:255], v[72:73], 0, v[68:69]
	global_load_dwordx4 v[250:253], v[254:255], off
	v_add_u32_e32 v103, v80, v66
	s_waitcnt vmcnt(14)
	ds_write_b128 v103, v[82:85]
	v_lshl_add_u64 v[254:255], v[70:71], 0, v[68:69]
	global_load_dwordx4 v[82:85], v[254:255], off
	v_add_u32_e32 v103, v81, v66
	s_waitcnt vmcnt(14)
	ds_write_b128 v103, v[86:89]
	v_add_u32_e32 v103, v79, v66
	s_waitcnt vmcnt(13)
	ds_write_b128 v103, v[200:203]
	v_add_u32_e32 v103, v78, v66
	s_waitcnt vmcnt(12)
	ds_write_b128 v103, v[204:207]
	v_add_u32_e32 v80, 0x8400, v80
	v_add_u32_e32 v81, 0x8400, v81
	v_add_u32_e32 v79, 0x8400, v79
	v_add_u32_e32 v78, 0x8400, v78
	v_add_u32_e32 v103, v80, v66
	s_waitcnt vmcnt(11)
	ds_write_b128 v103, v[208:211]
	v_add_u32_e32 v103, v81, v66
	s_waitcnt vmcnt(10)
	ds_write_b128 v103, v[212:215]
	v_add_u32_e32 v103, v79, v66
	s_waitcnt vmcnt(9)
	ds_write_b128 v103, v[216:219]
	v_add_u32_e32 v103, v78, v66
	s_waitcnt vmcnt(8)
	ds_write_b128 v103, v[220:223]
	v_add_u32_e32 v80, 0x8400, v80
	v_add_u32_e32 v81, 0x8400, v81
	v_add_u32_e32 v79, 0x8400, v79
	v_add_u32_e32 v78, 0x8400, v78
	v_add_u32_e32 v103, v80, v66
	s_waitcnt vmcnt(7)
	ds_write_b128 v103, v[224:227]
	v_add_u32_e32 v103, v81, v66
	s_waitcnt vmcnt(6)
	ds_write_b128 v103, v[228:231]
	v_add_u32_e32 v103, v79, v66
	s_waitcnt vmcnt(5)
	ds_write_b128 v103, v[232:235]
	v_add_u32_e32 v103, v78, v66
	s_waitcnt vmcnt(4)
	ds_write_b128 v103, v[236:239]
	v_add_u32_e32 v80, 0x8400, v80
	v_add_u32_e32 v81, 0x8400, v81
	v_add_u32_e32 v79, 0x8400, v79
	v_add_u32_e32 v78, 0x8400, v78
	v_add_u32_e32 v103, v80, v66
	s_waitcnt vmcnt(3)
	ds_write_b128 v103, v[240:243]
	v_add_u32_e32 v103, v81, v66
	s_waitcnt vmcnt(2)
	ds_write_b128 v103, v[244:247]
	v_add_u32_e32 v103, v79, v66
	s_waitcnt vmcnt(1)
	ds_write_b128 v103, v[250:253]
	v_add_u32_e32 v103, v78, v66
	s_waitcnt vmcnt(0)
	ds_write_b128 v103, v[82:85]
	s_or_b64 exec, exec, s[20:21]
	v_mul_f32_e32 v68, 0x3d800000, v6
	v_mul_f32_e32 v69, 0x3d800000, v7
	v_max3_f32 v68, v68, s41, v69
	v_mul_f32_e32 v69, 0x3d800000, v8
	v_mul_f32_e32 v70, 0x3d800000, v9
	v_max3_f32 v68, v68, v69, v70
	v_mul_f32_e32 v69, 0x3d800000, v2
	v_mul_f32_e32 v70, 0x3d800000, v3
	v_max3_f32 v68, v68, v69, v70
	v_mul_f32_e32 v69, 0x3d800000, v4
	v_mul_f32_e32 v70, 0x3d800000, v5
	v_max3_f32 v68, v68, v69, v70
	v_mul_f32_e32 v69, 0x3d800000, v10
	v_mul_f32_e32 v70, 0x3d800000, v11
	v_max3_f32 v68, v68, v69, v70
	v_mul_f32_e32 v69, 0x3d800000, v12
	v_mul_f32_e32 v70, 0x3d800000, v13
	v_max3_f32 v68, v68, v69, v70
	v_mul_f32_e32 v69, 0x3d800000, v14
	v_mul_f32_e32 v70, 0x3d800000, v15
	v_max3_f32 v68, v68, v69, v70
	v_mul_f32_e32 v69, 0x3d800000, v16
	v_mul_f32_e32 v70, 0x3d800000, v17
	v_max3_f32 v68, v68, v69, v70
	v_mul_f32_e32 v69, 0x3d800000, v18
	v_mul_f32_e32 v70, 0x3d800000, v19
	v_max3_f32 v68, v68, v69, v70
	v_mul_f32_e32 v69, 0x3d800000, v20
	v_mul_f32_e32 v70, 0x3d800000, v21
	v_max3_f32 v68, v68, v69, v70
	v_mul_f32_e32 v69, 0x3d800000, v22
	v_mul_f32_e32 v70, 0x3d800000, v23
	v_max3_f32 v68, v68, v69, v70
	v_mul_f32_e32 v69, 0x3d800000, v24
	v_mul_f32_e32 v70, 0x3d800000, v25
	v_max3_f32 v68, v68, v69, v70
	v_mul_f32_e32 v69, 0x3d800000, v26
	v_mul_f32_e32 v70, 0x3d800000, v27
	v_max3_f32 v68, v68, v69, v70
	v_mul_f32_e32 v69, 0x3d800000, v28
	v_mul_f32_e32 v70, 0x3d800000, v29
	v_max3_f32 v68, v68, v69, v70
	v_mul_f32_e32 v69, 0x3d800000, v30
	v_mul_f32_e32 v70, 0x3d800000, v31
	v_max3_f32 v68, v68, v69, v70
	v_mul_f32_e32 v69, 0x3d800000, v32
	v_mul_f32_e32 v70, 0x3d800000, v33
	v_max3_f32 v68, v68, v69, v70
	v_mul_f32_e32 v69, 0x3d800000, v34
	v_mul_f32_e32 v70, 0x3d800000, v35
	v_max3_f32 v68, v68, v69, v70
	v_mul_f32_e32 v69, 0x3d800000, v36
	v_mul_f32_e32 v70, 0x3d800000, v37
	v_max3_f32 v68, v68, v69, v70
	v_mul_f32_e32 v69, 0x3d800000, v38
	v_mul_f32_e32 v70, 0x3d800000, v39
	v_max3_f32 v68, v68, v69, v70
	v_mul_f32_e32 v69, 0x3d800000, v40
	v_mul_f32_e32 v70, 0x3d800000, v41
	v_max3_f32 v68, v68, v69, v70
	v_mul_f32_e32 v69, 0x3d800000, v42
	v_mul_f32_e32 v70, 0x3d800000, v43
	v_max3_f32 v68, v68, v69, v70
	v_mul_f32_e32 v69, 0x3d800000, v44
	v_mul_f32_e32 v70, 0x3d800000, v45
	v_max3_f32 v68, v68, v69, v70
	v_mul_f32_e32 v69, 0x3d800000, v46
	v_mul_f32_e32 v70, 0x3d800000, v47
	v_max3_f32 v68, v68, v69, v70
	v_mul_f32_e32 v69, 0x3d800000, v48
	v_mul_f32_e32 v70, 0x3d800000, v49
	v_max3_f32 v68, v68, v69, v70
	v_mul_f32_e32 v69, 0x3d800000, v50
	v_mul_f32_e32 v70, 0x3d800000, v51
	v_max3_f32 v68, v68, v69, v70
	v_mul_f32_e32 v69, 0x3d800000, v52
	v_mul_f32_e32 v70, 0x3d800000, v53
	v_max3_f32 v68, v68, v69, v70
	v_mul_f32_e32 v69, 0x3d800000, v54
	v_mul_f32_e32 v70, 0x3d800000, v55
	v_max3_f32 v68, v68, v69, v70
	v_mul_f32_e32 v69, 0x3d800000, v56
	v_mul_f32_e32 v70, 0x3d800000, v57
	v_max3_f32 v68, v68, v69, v70
	v_mul_f32_e32 v69, 0x3d800000, v58
	v_mul_f32_e32 v70, 0x3d800000, v59
	v_max3_f32 v68, v68, v69, v70
	v_mul_f32_e32 v69, 0x3d800000, v60
	v_mul_f32_e32 v70, 0x3d800000, v61
	v_max3_f32 v68, v68, v69, v70
	v_mul_f32_e32 v69, 0x3d800000, v62
	v_mul_f32_e32 v70, 0x3d800000, v63
	v_max3_f32 v68, v68, v69, v70
	v_mul_f32_e32 v69, 0x3d800000, v64
	v_mul_f32_e32 v70, 0x3d800000, v65
	v_max3_f32 v68, v68, v69, v70
	v_and_b32_e32 v70, 64, v189
	v_xor_b32_e32 v69, 16, v189
	v_add_u32_e32 v70, 64, v70
	v_cmp_lt_i32_e32 vcc, v69, v70
	s_lshl_b32 s20, s45, 8
	v_or_b32_e32 v74, s20, v183
	v_cndmask_b32_e32 v69, v189, v69, vcc
	v_lshlrev_b32_e32 v69, 2, v69
	ds_bpermute_b32 v71, v69, v68
	s_or_b32 s0, s46, 64
	s_and_b32 s21, s36, 0xf80
	v_add_lshl_u32 v72, v182, s20, 8
	v_add_lshl_u32 v66, v177, s20, 8
	s_waitcnt lgkmcnt(0)
	v_max_f32_e32 v71, v71, v71
	v_max_f32_e32 v75, v68, v71
	v_xor_b32_e32 v68, 32, v189
	v_cmp_lt_i32_e32 vcc, v68, v70
	v_lshlrev_b32_e32 v70, 1, v74
	v_and_b32_e32 v72, 0x1fc000, v72
	v_cndmask_b32_e32 v68, v189, v68, vcc
	v_lshlrev_b32_e32 v80, 2, v68
	ds_bpermute_b32 v76, v80, v75
	v_mov_b32_e32 v73, v91
	v_and_b32_e32 v90, 0x1fc000, v66
	v_or_b32_e32 v66, s20, v181
	v_add_lshl_u32 v68, v185, s20, 8
	s_waitcnt lgkmcnt(0)
	v_max_f32_e32 v74, v76, v76
	v_max_f32_e32 v78, v75, v74
	v_fma_f32 v2, v2, s40, -v78
	v_mul_f32_e32 v2, 0x3fb8aa3b, v2
	v_exp_f32_e32 v74, v2
	v_fma_f32 v2, v3, s40, -v78
	v_mul_f32_e32 v2, 0x3fb8aa3b, v2
	v_exp_f32_e32 v75, v2
	v_fma_f32 v2, v4, s40, -v78
	v_mul_f32_e32 v2, 0x3fb8aa3b, v2
	v_exp_f32_e32 v76, v2
	v_fma_f32 v2, v5, s40, -v78
	v_mul_f32_e32 v2, 0x3fb8aa3b, v2
	v_exp_f32_e32 v77, v2
	v_fma_f32 v2, v10, s40, -v78
	v_mul_f32_e32 v2, 0x3fb8aa3b, v2
	v_exp_f32_e32 v10, v2
	v_fma_f32 v2, v11, s40, -v78
	v_mul_f32_e32 v2, 0x3fb8aa3b, v2
	v_exp_f32_e32 v11, v2
	v_fma_f32 v2, v12, s40, -v78
	v_mul_f32_e32 v2, 0x3fb8aa3b, v2
	v_exp_f32_e32 v12, v2
	v_fma_f32 v2, v13, s40, -v78
	v_mul_f32_e32 v2, 0x3fb8aa3b, v2
	v_exp_f32_e32 v13, v2
	v_fma_f32 v2, v14, s40, -v78
	v_mul_f32_e32 v2, 0x3fb8aa3b, v2
	v_exp_f32_e32 v14, v2
	v_fma_f32 v2, v15, s40, -v78
	v_mul_f32_e32 v2, 0x3fb8aa3b, v2
	v_exp_f32_e32 v15, v2
	v_fma_f32 v2, v16, s40, -v78
	v_mul_f32_e32 v2, 0x3fb8aa3b, v2
	v_exp_f32_e32 v16, v2
	v_fma_f32 v2, v17, s40, -v78
	v_mul_f32_e32 v2, 0x3fb8aa3b, v2
	v_exp_f32_e32 v17, v2
	v_fma_f32 v2, v18, s40, -v78
	v_mul_f32_e32 v2, 0x3fb8aa3b, v2
	v_exp_f32_e32 v18, v2
	v_fma_f32 v2, v19, s40, -v78
	v_mul_f32_e32 v2, 0x3fb8aa3b, v2
	v_exp_f32_e32 v19, v2
	v_fma_f32 v2, v20, s40, -v78
	v_mul_f32_e32 v2, 0x3fb8aa3b, v2
	v_exp_f32_e32 v20, v2
	v_fma_f32 v2, v21, s40, -v78
	v_mul_f32_e32 v2, 0x3fb8aa3b, v2
	v_exp_f32_e32 v21, v2
	v_fma_f32 v2, v22, s40, -v78
	v_mul_f32_e32 v2, 0x3fb8aa3b, v2
	v_exp_f32_e32 v22, v2
	v_fma_f32 v2, v23, s40, -v78
	v_mul_f32_e32 v2, 0x3fb8aa3b, v2
	v_exp_f32_e32 v23, v2
	v_fma_f32 v2, v24, s40, -v78
	v_mul_f32_e32 v2, 0x3fb8aa3b, v2
	v_exp_f32_e32 v24, v2
	v_fma_f32 v2, v25, s40, -v78
	v_mul_f32_e32 v2, 0x3fb8aa3b, v2
	v_exp_f32_e32 v25, v2
	v_fma_f32 v2, v26, s40, -v78
	v_mul_f32_e32 v2, 0x3fb8aa3b, v2
	v_exp_f32_e32 v26, v2
	v_fma_f32 v2, v27, s40, -v78
	v_mul_f32_e32 v2, 0x3fb8aa3b, v2
	v_exp_f32_e32 v27, v2
	v_fma_f32 v2, v28, s40, -v78
	v_mul_f32_e32 v2, 0x3fb8aa3b, v2
	v_exp_f32_e32 v28, v2
	v_fma_f32 v2, v29, s40, -v78
	v_mul_f32_e32 v2, 0x3fb8aa3b, v2
	v_exp_f32_e32 v29, v2
	v_fma_f32 v2, v30, s40, -v78
	v_mul_f32_e32 v2, 0x3fb8aa3b, v2
	v_exp_f32_e32 v30, v2
	v_fma_f32 v2, v31, s40, -v78
	v_mul_f32_e32 v2, 0x3fb8aa3b, v2
	v_exp_f32_e32 v31, v2
	v_fma_f32 v2, v32, s40, -v78
	v_mul_f32_e32 v2, 0x3fb8aa3b, v2
	v_exp_f32_e32 v32, v2
	v_fma_f32 v2, v33, s40, -v78
	v_mul_f32_e32 v2, 0x3fb8aa3b, v2
	v_exp_f32_e32 v33, v2
	v_fma_f32 v2, v34, s40, -v78
	v_mul_f32_e32 v2, 0x3fb8aa3b, v2
	v_exp_f32_e32 v34, v2
	v_fma_f32 v2, v35, s40, -v78
	v_mul_f32_e32 v2, 0x3fb8aa3b, v2
	v_exp_f32_e32 v35, v2
	v_fma_f32 v2, v36, s40, -v78
	v_mul_f32_e32 v2, 0x3fb8aa3b, v2
	v_exp_f32_e32 v36, v2
	v_fma_f32 v2, v37, s40, -v78
	v_mul_f32_e32 v2, 0x3fb8aa3b, v2
	v_exp_f32_e32 v37, v2
	v_fma_f32 v2, v38, s40, -v78
	v_mul_f32_e32 v2, 0x3fb8aa3b, v2
	v_exp_f32_e32 v38, v2
	v_fma_f32 v2, v39, s40, -v78
	v_mul_f32_e32 v2, 0x3fb8aa3b, v2
	v_exp_f32_e32 v39, v2
	v_fma_f32 v2, v40, s40, -v78
	v_mul_f32_e32 v2, 0x3fb8aa3b, v2
	v_exp_f32_e32 v40, v2
	v_fma_f32 v2, v41, s40, -v78
	v_mul_f32_e32 v2, 0x3fb8aa3b, v2
	v_exp_f32_e32 v41, v2
	v_fma_f32 v2, v42, s40, -v78
	v_mul_f32_e32 v2, 0x3fb8aa3b, v2
	v_exp_f32_e32 v42, v2
	v_fma_f32 v2, v43, s40, -v78
	v_mul_f32_e32 v2, 0x3fb8aa3b, v2
	v_exp_f32_e32 v43, v2
	v_fma_f32 v2, v44, s40, -v78
	v_mul_f32_e32 v2, 0x3fb8aa3b, v2
	v_exp_f32_e32 v44, v2
	v_fma_f32 v2, v45, s40, -v78
	v_mul_f32_e32 v2, 0x3fb8aa3b, v2
	v_exp_f32_e32 v45, v2
	v_fma_f32 v2, v46, s40, -v78
	v_mul_f32_e32 v2, 0x3fb8aa3b, v2
	v_exp_f32_e32 v46, v2
	v_fma_f32 v2, v47, s40, -v78
	v_mul_f32_e32 v2, 0x3fb8aa3b, v2
	v_exp_f32_e32 v47, v2
	v_fma_f32 v2, v48, s40, -v78
	v_mul_f32_e32 v2, 0x3fb8aa3b, v2
	v_exp_f32_e32 v48, v2
	v_fma_f32 v2, v49, s40, -v78
	v_mul_f32_e32 v2, 0x3fb8aa3b, v2
	v_exp_f32_e32 v49, v2
	v_fma_f32 v2, v50, s40, -v78
	v_mul_f32_e32 v2, 0x3fb8aa3b, v2
	v_exp_f32_e32 v50, v2
	v_fma_f32 v2, v51, s40, -v78
	v_mul_f32_e32 v2, 0x3fb8aa3b, v2
	v_exp_f32_e32 v51, v2
	v_fma_f32 v2, v52, s40, -v78
	v_mul_f32_e32 v2, 0x3fb8aa3b, v2
	v_exp_f32_e32 v52, v2
	v_fma_f32 v2, v53, s40, -v78
	v_mul_f32_e32 v2, 0x3fb8aa3b, v2
	v_exp_f32_e32 v53, v2
	v_fma_f32 v2, v54, s40, -v78
	v_mul_f32_e32 v2, 0x3fb8aa3b, v2
	v_exp_f32_e32 v54, v2
	v_fma_f32 v2, v55, s40, -v78
	v_mul_f32_e32 v2, 0x3fb8aa3b, v2
	v_exp_f32_e32 v55, v2
	v_fma_f32 v2, v56, s40, -v78
	v_mul_f32_e32 v2, 0x3fb8aa3b, v2
	v_exp_f32_e32 v56, v2
	v_fma_f32 v2, v57, s40, -v78
	v_mul_f32_e32 v2, 0x3fb8aa3b, v2
	v_exp_f32_e32 v57, v2
	v_fma_f32 v2, v58, s40, -v78
	v_mul_f32_e32 v2, 0x3fb8aa3b, v2
	v_exp_f32_e32 v58, v2
	v_fma_f32 v2, v59, s40, -v78
	v_mul_f32_e32 v2, 0x3fb8aa3b, v2
	v_exp_f32_e32 v59, v2
	v_fma_f32 v2, v60, s40, -v78
	v_mul_f32_e32 v2, 0x3fb8aa3b, v2
	v_exp_f32_e32 v60, v2
	v_fma_f32 v2, v61, s40, -v78
	v_mul_f32_e32 v2, 0x3fb8aa3b, v2
	v_exp_f32_e32 v61, v2
	v_fma_f32 v2, v62, s40, -v78
	v_mul_f32_e32 v2, 0x3fb8aa3b, v2
	v_fma_f32 v6, v6, s40, -v78
	v_exp_f32_e32 v62, v2
	v_fma_f32 v2, v63, s40, -v78
	v_mul_f32_e32 v6, 0x3fb8aa3b, v6
	v_fma_f32 v7, v7, s40, -v78
	v_mul_f32_e32 v2, 0x3fb8aa3b, v2
	v_exp_f32_e32 v6, v6
	v_mul_f32_e32 v7, 0x3fb8aa3b, v7
	v_fma_f32 v8, v8, s40, -v78
	v_exp_f32_e32 v63, v2
	v_fma_f32 v2, v64, s40, -v78
	v_exp_f32_e32 v7, v7
	v_mul_f32_e32 v8, 0x3fb8aa3b, v8
	v_fma_f32 v9, v9, s40, -v78
	v_mul_f32_e32 v2, 0x3fb8aa3b, v2
	v_exp_f32_e32 v8, v8
	v_mul_f32_e32 v9, 0x3fb8aa3b, v9
	v_exp_f32_e32 v64, v2
	v_fma_f32 v2, v65, s40, -v78
	v_exp_f32_e32 v9, v9
	v_mul_f32_e32 v2, 0x3fb8aa3b, v2
	v_exp_f32_e32 v65, v2
	v_add_f32_e32 v2, 0, v6
	v_add_f32_e32 v2, v7, v2
	v_add_f32_e32 v2, v8, v2
	v_add_f32_e32 v2, v9, v2
	v_add_f32_e32 v2, v74, v2
	v_add_f32_e32 v2, v75, v2
	v_add_f32_e32 v2, v76, v2
	v_add_f32_e32 v2, v77, v2
	v_add_f32_e32 v2, v10, v2
	v_add_f32_e32 v2, v11, v2
	v_add_f32_e32 v2, v12, v2
	v_add_f32_e32 v2, v13, v2
	v_add_f32_e32 v2, v14, v2
	v_add_f32_e32 v2, v15, v2
	v_add_f32_e32 v2, v16, v2
	v_add_f32_e32 v2, v17, v2
	v_add_f32_e32 v2, v18, v2
	v_add_f32_e32 v2, v19, v2
	v_add_f32_e32 v2, v20, v2
	v_add_f32_e32 v2, v21, v2
	v_add_f32_e32 v2, v22, v2
	v_add_f32_e32 v2, v23, v2
	v_add_f32_e32 v2, v24, v2
	v_add_f32_e32 v2, v25, v2
	v_add_f32_e32 v2, v26, v2
	v_add_f32_e32 v2, v27, v2
	v_add_f32_e32 v2, v28, v2
	v_add_f32_e32 v2, v29, v2
	v_add_f32_e32 v2, v30, v2
	v_add_f32_e32 v2, v31, v2
	v_add_f32_e32 v2, v32, v2
	v_add_f32_e32 v2, v33, v2
	v_add_f32_e32 v2, v34, v2
	v_add_f32_e32 v2, v35, v2
	v_add_f32_e32 v2, v36, v2
	v_add_f32_e32 v2, v37, v2
	v_add_f32_e32 v2, v38, v2
	v_add_f32_e32 v2, v39, v2
	v_add_f32_e32 v2, v40, v2
	v_add_f32_e32 v2, v41, v2
	v_add_f32_e32 v2, v42, v2
	v_add_f32_e32 v2, v43, v2
	v_add_f32_e32 v2, v44, v2
	v_add_f32_e32 v2, v45, v2
	v_add_f32_e32 v2, v46, v2
	v_add_f32_e32 v2, v47, v2
	v_add_f32_e32 v2, v48, v2
	v_add_f32_e32 v2, v49, v2
	v_add_f32_e32 v2, v50, v2
	v_add_f32_e32 v2, v51, v2
	v_add_f32_e32 v2, v52, v2
	v_add_f32_e32 v2, v53, v2
	v_add_f32_e32 v2, v54, v2
	v_add_f32_e32 v2, v55, v2
	v_add_f32_e32 v2, v56, v2
	v_add_f32_e32 v2, v57, v2
	v_add_f32_e32 v2, v58, v2
	v_add_f32_e32 v2, v59, v2
	v_add_f32_e32 v2, v60, v2
	v_add_f32_e32 v2, v61, v2
	v_add_f32_e32 v2, v62, v2
	v_add_f32_e32 v2, v63, v2
	v_add_f32_e32 v2, v64, v2
	v_add_f32_e32 v2, v65, v2
	ds_bpermute_b32 v3, v69, v2
	v_or_b32_e32 v4, s20, v186
	v_lshlrev_b32_e32 v78, 1, v4
	v_or_b32_e32 v4, s20, v173
	v_mov_b32_e32 v83, v91
	s_waitcnt lgkmcnt(0)
	v_add_f32_e32 v2, v2, v3
	ds_bpermute_b32 v3, v80, v2
	v_lshlrev_b32_e32 v80, 1, v4
	v_add_lshl_u32 v4, v187, s20, 8
	v_and_b32_e32 v82, 0x1fc000, v4
	v_lshlrev_b32_e32 v66, 1, v66
	s_waitcnt lgkmcnt(0)
	v_add_f32_e32 v2, v2, v3
	v_div_scale_f32 v3, s[22:23], v2, v2, 1.0
	v_rcp_f32_e32 v5, v3
	s_ashr_i32 s22, s44, 7
	s_ashr_i32 s23, s22, 31
	s_lshl_b64 s[22:23], s[22:23], 20
	v_fma_f32 v4, -v3, v5, 1.0
	v_fmac_f32_e32 v5, v4, v5
	v_div_scale_f32 v4, vcc, 1.0, v2, 1.0
	v_mul_f32_e32 v84, v4, v5
	v_fma_f32 v85, -v3, v84, v4
	v_fmac_f32_e32 v84, v85, v5
	v_fma_f32 v3, -v3, v84, v4
	v_div_fmas_f32 v3, v3, v5, v84
	v_div_fixup_f32 v84, v3, v2, 1.0
	v_pk_mul_f32 v[2:3], v[6:7], v[84:85] op_sel_hi:[1,0]
	v_pk_mul_f32 v[4:5], v[8:9], v[84:85] op_sel_hi:[1,0]
	v_cvt_pk_bf16_f32 v2, v2, v3
	v_cvt_pk_bf16_f32 v3, v4, v5
	v_pk_mul_f32 v[4:5], v[74:75], v[84:85] op_sel_hi:[1,0]
	v_pk_mul_f32 v[6:7], v[76:77], v[84:85] op_sel_hi:[1,0]
	v_cvt_pk_bf16_f32 v4, v4, v5
	v_cvt_pk_bf16_f32 v5, v6, v7
	v_pk_mul_f32 v[6:7], v[10:11], v[84:85] op_sel_hi:[1,0]
	v_pk_mul_f32 v[8:9], v[12:13], v[84:85] op_sel_hi:[1,0]
	v_cvt_pk_bf16_f32 v6, v6, v7
	v_cvt_pk_bf16_f32 v7, v8, v9
	v_pk_mul_f32 v[8:9], v[14:15], v[84:85] op_sel_hi:[1,0]
	v_pk_mul_f32 v[10:11], v[16:17], v[84:85] op_sel_hi:[1,0]
	v_cvt_pk_bf16_f32 v8, v8, v9
	v_cvt_pk_bf16_f32 v9, v10, v11
	v_pk_mul_f32 v[10:11], v[18:19], v[84:85] op_sel_hi:[1,0]
	v_pk_mul_f32 v[12:13], v[20:21], v[84:85] op_sel_hi:[1,0]
	v_cvt_pk_bf16_f32 v10, v10, v11
	v_cvt_pk_bf16_f32 v11, v12, v13
	v_pk_mul_f32 v[12:13], v[22:23], v[84:85] op_sel_hi:[1,0]
	v_pk_mul_f32 v[14:15], v[24:25], v[84:85] op_sel_hi:[1,0]
	v_cvt_pk_bf16_f32 v12, v12, v13
	v_cvt_pk_bf16_f32 v13, v14, v15
	v_pk_mul_f32 v[14:15], v[26:27], v[84:85] op_sel_hi:[1,0]
	v_pk_mul_f32 v[16:17], v[28:29], v[84:85] op_sel_hi:[1,0]
	v_cvt_pk_bf16_f32 v14, v14, v15
	v_cvt_pk_bf16_f32 v15, v16, v17
	v_pk_mul_f32 v[16:17], v[30:31], v[84:85] op_sel_hi:[1,0]
	v_pk_mul_f32 v[18:19], v[32:33], v[84:85] op_sel_hi:[1,0]
	v_cvt_pk_bf16_f32 v16, v16, v17
	v_cvt_pk_bf16_f32 v17, v18, v19
	v_pk_mul_f32 v[18:19], v[34:35], v[84:85] op_sel_hi:[1,0]
	v_pk_mul_f32 v[20:21], v[36:37], v[84:85] op_sel_hi:[1,0]
	v_cvt_pk_bf16_f32 v18, v18, v19
	v_cvt_pk_bf16_f32 v19, v20, v21
	v_pk_mul_f32 v[20:21], v[38:39], v[84:85] op_sel_hi:[1,0]
	v_pk_mul_f32 v[22:23], v[40:41], v[84:85] op_sel_hi:[1,0]
	v_cvt_pk_bf16_f32 v20, v20, v21
	v_cvt_pk_bf16_f32 v21, v22, v23
	v_pk_mul_f32 v[22:23], v[42:43], v[84:85] op_sel_hi:[1,0]
	v_pk_mul_f32 v[24:25], v[44:45], v[84:85] op_sel_hi:[1,0]
	v_cvt_pk_bf16_f32 v22, v22, v23
	v_cvt_pk_bf16_f32 v23, v24, v25
	v_pk_mul_f32 v[24:25], v[46:47], v[84:85] op_sel_hi:[1,0]
	v_pk_mul_f32 v[26:27], v[48:49], v[84:85] op_sel_hi:[1,0]
	v_cvt_pk_bf16_f32 v24, v24, v25
	v_cvt_pk_bf16_f32 v25, v26, v27
	v_pk_mul_f32 v[26:27], v[50:51], v[84:85] op_sel_hi:[1,0]
	v_pk_mul_f32 v[28:29], v[52:53], v[84:85] op_sel_hi:[1,0]
	v_cvt_pk_bf16_f32 v26, v26, v27
	v_cvt_pk_bf16_f32 v27, v28, v29
	v_pk_mul_f32 v[28:29], v[54:55], v[84:85] op_sel_hi:[1,0]
	v_pk_mul_f32 v[30:31], v[56:57], v[84:85] op_sel_hi:[1,0]
	s_add_u32 s24, s22, 0xf000400
	v_cvt_pk_bf16_f32 v28, v28, v29
	v_cvt_pk_bf16_f32 v29, v30, v31
	v_pk_mul_f32 v[30:31], v[58:59], v[84:85] op_sel_hi:[1,0]
	v_pk_mul_f32 v[32:33], v[60:61], v[84:85] op_sel_hi:[1,0]
	s_addc_u32 s25, s23, 0
	s_add_i32 s21, s21, s43
	v_cvt_pk_bf16_f32 v30, v30, v31
	v_cvt_pk_bf16_f32 v31, v32, v33
	v_pk_mul_f32 v[32:33], v[62:63], v[84:85] op_sel_hi:[1,0]
	v_pk_mul_f32 v[34:35], v[64:65], v[84:85] op_sel_hi:[1,0]
	v_add_u32_e32 v40, s21, v180
	v_cvt_pk_bf16_f32 v32, v32, v33
	v_cvt_pk_bf16_f32 v33, v34, v35
	v_lshlrev_b32_e32 v34, 6, v190
	v_mad_i64_i32 v[46:47], s[26:27], v40, s39, v[104:105]
	v_lshlrev_b32_e32 v40, 2, v40
	v_and_b32_e32 v50, 0x3c0, v34
	v_lshlrev_b32_e32 v34, 2, v190
	v_lshl_add_u64 v[38:39], s[24:25], 0, v[72:73]
	v_and_b32_e32 v52, 32, v40
	s_add_u32 s22, s22, 0xf000000
	v_and_b32_e32 v51, 32, v34
	v_lshl_add_u64 v[34:35], s[24:25], 0, v[90:91]
	v_and_or_b32 v38, v70, 24, v38
	v_add_u32_e32 v90, v184, v52
	s_addc_u32 s23, s23, 0
	v_mov_b32_e32 v67, v91
	v_mov_b32_e32 v71, v91
	v_and_b32_e32 v68, 0x1fc000, v68
	v_mov_b32_e32 v69, v91
	v_mov_b32_e32 v79, v91
	v_mov_b32_e32 v81, v91
	v_lshl_add_u64 v[38:39], v[38:39], 0, v[90:91]
	v_lshl_add_u64 v[48:49], s[22:23], 0, v[82:83]
	v_add_u32_e32 v90, v188, v52
	s_mov_b32 s20, 16
	v_lshl_add_u64 v[36:37], v[46:47], 0, v[66:67]
	v_lshl_add_u64 v[40:41], v[46:47], 0, v[70:71]
	v_lshl_add_u64 v[42:43], s[22:23], 0, v[68:69]
	v_lshl_add_u64 v[44:45], v[46:47], 0, v[78:79]
	v_lshl_add_u64 v[46:47], v[46:47], 0, v[80:81]
	v_lshl_add_u64 v[48:49], v[48:49], 0, v[90:91]
	v_mov_b32_e32 v52, v107
	v_lshl_add_u64 v[234:235], s[92:93], 0, v[46:47]
	global_load_dwordx2 v[200:201], v[234:235], off
	global_load_dwordx2 v[208:209], v[234:235], off offset:128
	global_load_dwordx2 v[216:217], v[234:235], off offset:256
	global_load_dwordx2 v[224:225], v[234:235], off offset:384
	v_lshl_add_u64 v[234:235], s[92:93], 0, v[44:45]
	global_load_dwordx2 v[202:203], v[234:235], off
	global_load_dwordx2 v[210:211], v[234:235], off offset:128
	global_load_dwordx2 v[218:219], v[234:235], off offset:256
	global_load_dwordx2 v[226:227], v[234:235], off offset:384
	v_lshl_add_u64 v[234:235], s[92:93], 0, v[40:41]
	global_load_dwordx2 v[204:205], v[234:235], off
	global_load_dwordx2 v[212:213], v[234:235], off offset:128
	global_load_dwordx2 v[220:221], v[234:235], off offset:256
	global_load_dwordx2 v[228:229], v[234:235], off offset:384
	v_lshl_add_u64 v[234:235], s[92:93], 0, v[36:37]
	global_load_dwordx2 v[206:207], v[234:235], off
	global_load_dwordx2 v[214:215], v[234:235], off offset:128
	global_load_dwordx2 v[222:223], v[234:235], off offset:256
	global_load_dwordx2 v[230:231], v[234:235], off offset:384
	s_barrier
